# gather unit: gate value loaded before the row gather instead of after the final barrier
# baseline (speedup 1.0000x reference)
.LBB0_2331:
	s_or_b64 exec, exec, s[20:21]
	v_lshl_add_u32 v0, s55, 11, v213
	s_lshl_b32 s30, s23, 1
	ds_write_b128 v0, v[12:15] offset:12288
	ds_write_b128 v0, v[4:7] offset:12304
	v_lshl_add_u64 v[0:1], v[152:153], 0, s[30:31]
	s_waitcnt lgkmcnt(0)
	s_barrier
	v_mov_b32_e32 v27, v243
	v_add_u32_e32 v12, 0x8000, v215
	ds_read2_b64 v[0:3], v12 offset1:8
	ds_read2_b64 v[4:7], v12 offset0:16 offset1:24
	ds_read2_b64 v[8:11], v12 offset0:32 offset1:40
	ds_read2_b64 v[12:15], v12 offset0:48 offset1:56
	ds_read2st64_b32 v[16:17], v216 offset0:48 offset1:56
	ds_read2st64_b32 v[18:19], v216 offset0:64 offset1:72
	ds_read2st64_b32 v[20:21], v216 offset0:80 offset1:88
	ds_read2st64_b32 v[22:23], v216 offset0:96 offset1:104
	s_waitcnt lgkmcnt(7)
	v_max3_f32 v26, v0, s44, v2
	s_waitcnt lgkmcnt(6)
	v_max3_f32 v26, v26, v4, v6
	s_waitcnt lgkmcnt(5)
	v_max3_f32 v26, v26, v8, v10
	s_waitcnt lgkmcnt(4)
	v_max3_f32 v26, v26, v12, v14
	v_sub_f32_e32 v28, v0, v26
	v_sub_f32_e32 v29, v2, v26
	s_waitcnt lgkmcnt(3)
	v_mov_b32_e32 v0, v16
	v_exp_f32_e32 v16, v28
	v_sub_f32_e32 v30, v4, v26
	s_waitcnt lgkmcnt(2)
	v_mov_b32_e32 v4, v18
	v_exp_f32_e32 v18, v29
	v_sub_f32_e32 v31, v6, v26
	v_sub_f32_e32 v32, v8, v26
	s_waitcnt lgkmcnt(1)
	v_mov_b32_e32 v8, v20
	v_exp_f32_e32 v20, v30
	v_sub_f32_e32 v34, v12, v26
	s_waitcnt lgkmcnt(0)
	v_mov_b32_e32 v12, v22
	v_exp_f32_e32 v22, v31
	v_sub_f32_e32 v33, v10, v26
	v_sub_f32_e32 v35, v14, v26
	v_mov_b32_e32 v2, v17
	v_exp_f32_e32 v26, v32
	v_pk_fma_f32 v[0:1], v[0:1], v[16:17], 0 op_sel_hi:[1,0,0]
	v_exp_f32_e32 v28, v33
	v_pk_fma_f32 v[0:1], v[18:19], v[2:3], v[0:1] op_sel_hi:[0,1,1]
	v_mov_b32_e32 v6, v19
	v_exp_f32_e32 v30, v34
	v_pk_fma_f32 v[0:1], v[20:21], v[4:5], v[0:1] op_sel_hi:[0,1,1]
	v_exp_f32_e32 v32, v35
	v_pk_fma_f32 v[0:1], v[22:23], v[6:7], v[0:1] op_sel_hi:[0,1,1]
	v_mov_b32_e32 v10, v21
	v_mov_b32_e32 v14, v23
	s_add_i32 s54, s54, s56
	s_lshl_b32 s30, s22, 1
	v_lshl_add_u64 v[24:25], v[154:155], 0, s[30:31]
	s_cmpk_lt_i32 s54, 0x100
	s_waitcnt vmcnt(0)
	v_pk_fma_f32 v[0:1], v[26:27], v[8:9], v[0:1] op_sel_hi:[0,1,1]
	v_pk_fma_f32 v[0:1], v[28:29], v[10:11], v[0:1] op_sel_hi:[0,1,1]
	v_pk_fma_f32 v[0:1], v[30:31], v[12:13], v[0:1] op_sel_hi:[0,1,1]
	v_pk_fma_f32 v[0:1], v[32:33], v[14:15], v[0:1] op_sel_hi:[0,1,1]
	v_div_scale_f32 v2, s[20:21], v1, v1, v0
	v_rcp_f32_e32 v3, v2
	v_div_scale_f32 v4, vcc, v0, v1, v0
	v_fma_f32 v5, -v2, v3, 1.0
	v_fmac_f32_e32 v3, v5, v3
	v_mul_f32_e32 v5, v4, v3
	v_fma_f32 v6, -v2, v5, v4
	v_fmac_f32_e32 v5, v6, v3
	v_fma_f32 v2, -v2, v5, v4
	v_div_fmas_f32 v2, v2, v3, v5
	v_div_fixup_f32 v0, v2, v1, v0
	v_lshlrev_b32_e32 v1, 16, v27
	v_mul_f32_e32 v0, v0, v1
	v_bfe_u32 v1, v0, 16, 1
	v_add3_u32 v0, v0, v1, s53
	global_store_short_d16_hi v[24:25], v0, off
	s_barrier
	s_cbranch_scc0 .LBB0_2477

.LBB0_2455:
	v_mov_b32_e32 v139, v138
	s_waitcnt vmcnt(3)
	v_mov_b64_e32 v[122:123], v[22:23]
	s_waitcnt vmcnt(2)
	v_mov_b64_e32 v[126:127], v[30:31]
	v_mov_b64_e32 v[106:107], v[38:39]
	v_mov_b64_e32 v[110:111], v[46:47]
	v_mov_b64_e32 v[90:91], v[54:55]
	v_mov_b64_e32 v[94:95], v[70:71]
	v_mov_b64_e32 v[56:57], v[72:73]
	v_mov_b64_e32 v[60:61], v[84:85]
	s_waitcnt vmcnt(1)
	v_mov_b64_e32 v[130:131], v[2:3]
	s_waitcnt vmcnt(0)
	v_mov_b64_e32 v[134:135], v[10:11]
	v_mov_b64_e32 v[114:115], v[18:19]
	v_mov_b64_e32 v[118:119], v[26:27]
	v_mov_b64_e32 v[98:99], v[34:35]
	v_mov_b64_e32 v[102:103], v[42:43]
	v_mov_b64_e32 v[78:79], v[50:51]
	v_mov_b64_e32 v[82:83], v[66:67]
	s_lshl_b32 s23, s58, 9
	s_lshl_b32 s98, s23, 1
	s_mov_b32 s99, 0
	v_lshl_add_u64 v[244:245], v[152:153], 0, s[98:99]
	global_load_ushort v243, v[244:245], off
	v_lshlrev_b32_e32 v156, 16, v4
	v_and_b32_e32 v157, 0xffff0000, v5
	v_and_b32_e32 v158, 0xffff0000, v4
	v_lshlrev_b32_e32 v159, 16, v5
	v_lshlrev_b32_e32 v161, 16, v7
	v_lshlrev_b32_e32 v160, 16, v6
	v_and_b32_e32 v163, 0xffff0000, v7
	v_and_b32_e32 v162, 0xffff0000, v6
	s_addk_i32 s20, 0x7020
	s_mov_b32 s21, 0
	v_mov_b32_e32 v177, 0xff800000
	v_mov_b32_e32 v176, 0
	v_mov_b64_e32 v[12:13], v[138:139]
	v_mov_b64_e32 v[14:15], v[138:139]
	v_mov_b64_e32 v[4:5], v[138:139]
	v_mov_b64_e32 v[6:7], v[138:139]
	v_mov_b64_e32 v[178:179], v[166:167]
	v_mov_b64_e32 v[174:175], v[170:171]
	v_mov_b64_e32 v[168:169], v[172:173]
	v_mov_b64_e32 v[120:121], v[20:21]
	v_mov_b64_e32 v[124:125], v[28:29]
	v_mov_b64_e32 v[104:105], v[36:37]
	v_mov_b64_e32 v[108:109], v[44:45]
	v_mov_b64_e32 v[88:89], v[52:53]
	v_mov_b64_e32 v[92:93], v[68:69]
	v_mov_b64_e32 v[58:59], v[74:75]
	v_mov_b64_e32 v[62:63], v[86:87]
	v_mov_b64_e32 v[128:129], v[0:1]
	v_mov_b64_e32 v[132:133], v[8:9]
	v_mov_b64_e32 v[112:113], v[16:17]
	v_mov_b64_e32 v[116:117], v[24:25]
	v_mov_b64_e32 v[96:97], v[32:33]
	v_mov_b64_e32 v[100:101], v[40:41]
	v_mov_b64_e32 v[76:77], v[48:49]
	v_mov_b64_e32 v[80:81], v[64:65]
	v_mov_b64_e32 v[180:181], v[164:165]
	s_cmpk_eq_i32 s21, 0xe0
	s_cbranch_scc1 .LBB0_2467
	s_branch .LBB0_2457

.LBB0_2702:
	s_or_b64 exec, exec, s[20:21]
	v_lshl_add_u32 v0, s59, 11, v213
	s_lshl_b32 s30, s23, 1
	ds_write_b128 v0, v[12:15] offset:12288
	ds_write_b128 v0, v[4:7] offset:12304
	v_lshl_add_u64 v[0:1], v[152:153], 0, s[30:31]
	s_waitcnt lgkmcnt(0)
	s_barrier
	v_mov_b32_e32 v27, v243
	v_add_u32_e32 v12, 0x8000, v215
	ds_read2_b64 v[0:3], v12 offset1:8
	ds_read2_b64 v[4:7], v12 offset0:16 offset1:24
	ds_read2_b64 v[8:11], v12 offset0:32 offset1:40
	ds_read2_b64 v[12:15], v12 offset0:48 offset1:56
	ds_read2st64_b32 v[16:17], v216 offset0:48 offset1:56
	ds_read2st64_b32 v[18:19], v216 offset0:64 offset1:72
	ds_read2st64_b32 v[20:21], v216 offset0:80 offset1:88
	ds_read2st64_b32 v[22:23], v216 offset0:96 offset1:104
	s_waitcnt lgkmcnt(7)
	v_max3_f32 v26, v0, s46, v2
	s_waitcnt lgkmcnt(6)
	v_max3_f32 v26, v26, v4, v6
	s_waitcnt lgkmcnt(5)
	v_max3_f32 v26, v26, v8, v10
	s_waitcnt lgkmcnt(4)
	v_max3_f32 v26, v26, v12, v14
	v_sub_f32_e32 v28, v0, v26
	v_sub_f32_e32 v29, v2, v26
	s_waitcnt lgkmcnt(3)
	v_mov_b32_e32 v0, v16
	v_exp_f32_e32 v16, v28
	v_sub_f32_e32 v30, v4, v26
	s_waitcnt lgkmcnt(2)
	v_mov_b32_e32 v4, v18
	v_exp_f32_e32 v18, v29
	v_sub_f32_e32 v31, v6, v26
	v_sub_f32_e32 v32, v8, v26
	s_waitcnt lgkmcnt(1)
	v_mov_b32_e32 v8, v20
	v_exp_f32_e32 v20, v30
	v_sub_f32_e32 v34, v12, v26
	s_waitcnt lgkmcnt(0)
	v_mov_b32_e32 v12, v22
	v_exp_f32_e32 v22, v31
	v_sub_f32_e32 v33, v10, v26
	v_sub_f32_e32 v35, v14, v26
	v_mov_b32_e32 v2, v17
	v_exp_f32_e32 v26, v32
	v_pk_fma_f32 v[0:1], v[0:1], v[16:17], 0 op_sel_hi:[1,0,0]
	v_exp_f32_e32 v28, v33
	v_pk_fma_f32 v[0:1], v[18:19], v[2:3], v[0:1] op_sel_hi:[0,1,1]
	v_mov_b32_e32 v6, v19
	v_exp_f32_e32 v30, v34
	v_pk_fma_f32 v[0:1], v[20:21], v[4:5], v[0:1] op_sel_hi:[0,1,1]
	v_exp_f32_e32 v32, v35
	v_pk_fma_f32 v[0:1], v[22:23], v[6:7], v[0:1] op_sel_hi:[0,1,1]
	v_mov_b32_e32 v10, v21
	v_mov_b32_e32 v14, v23
	s_add_i32 s58, s58, s56
	s_lshl_b32 s30, s22, 1
	v_lshl_add_u64 v[24:25], v[154:155], 0, s[30:31]
	s_cmpk_gt_i32 s58, 0xff
	s_waitcnt vmcnt(0)
	v_pk_fma_f32 v[0:1], v[26:27], v[8:9], v[0:1] op_sel_hi:[0,1,1]
	v_pk_fma_f32 v[0:1], v[28:29], v[10:11], v[0:1] op_sel_hi:[0,1,1]
	v_pk_fma_f32 v[0:1], v[30:31], v[12:13], v[0:1] op_sel_hi:[0,1,1]
	v_pk_fma_f32 v[0:1], v[32:33], v[14:15], v[0:1] op_sel_hi:[0,1,1]
	v_div_scale_f32 v2, s[20:21], v1, v1, v0
	v_rcp_f32_e32 v3, v2
	v_div_scale_f32 v4, vcc, v0, v1, v0
	v_fma_f32 v5, -v2, v3, 1.0
	v_fmac_f32_e32 v3, v5, v3
	v_mul_f32_e32 v5, v4, v3
	v_fma_f32 v6, -v2, v5, v4
	v_fmac_f32_e32 v5, v6, v3
	v_fma_f32 v2, -v2, v5, v4
	v_div_fmas_f32 v2, v2, v3, v5
	v_div_fixup_f32 v0, v2, v1, v0
	v_lshlrev_b32_e32 v1, 16, v27
	v_mul_f32_e32 v0, v0, v1
	v_bfe_u32 v1, v0, 16, 1
	v_add3_u32 v0, v0, v1, s55
	global_store_short_d16_hi v[24:25], v0, off
	s_barrier
	s_cbranch_scc1 .LBB0_2848

.LBB0_2826:
	v_mov_b32_e32 v139, v138
	s_waitcnt vmcnt(3)
	v_mov_b64_e32 v[122:123], v[22:23]
	s_waitcnt vmcnt(2)
	v_mov_b64_e32 v[126:127], v[30:31]
	v_mov_b64_e32 v[106:107], v[38:39]
	v_mov_b64_e32 v[110:111], v[46:47]
	v_mov_b64_e32 v[90:91], v[54:55]
	v_mov_b64_e32 v[94:95], v[70:71]
	v_mov_b64_e32 v[56:57], v[72:73]
	v_mov_b64_e32 v[60:61], v[84:85]
	s_waitcnt vmcnt(1)
	v_mov_b64_e32 v[130:131], v[2:3]
	s_waitcnt vmcnt(0)
	v_mov_b64_e32 v[134:135], v[10:11]
	v_mov_b64_e32 v[114:115], v[18:19]
	v_mov_b64_e32 v[118:119], v[26:27]
	v_mov_b64_e32 v[98:99], v[34:35]
	v_mov_b64_e32 v[102:103], v[42:43]
	v_mov_b64_e32 v[78:79], v[50:51]
	v_mov_b64_e32 v[82:83], v[66:67]
	s_lshl_b32 s23, s60, 9
	s_lshl_b32 s98, s23, 1
	s_mov_b32 s99, 0
	v_lshl_add_u64 v[244:245], v[152:153], 0, s[98:99]
	global_load_ushort v243, v[244:245], off
	v_lshlrev_b32_e32 v156, 16, v4
	v_and_b32_e32 v157, 0xffff0000, v5
	v_and_b32_e32 v158, 0xffff0000, v4
	v_lshlrev_b32_e32 v159, 16, v5
	v_lshlrev_b32_e32 v161, 16, v7
	v_lshlrev_b32_e32 v160, 16, v6
	v_and_b32_e32 v163, 0xffff0000, v7
	v_and_b32_e32 v162, 0xffff0000, v6
	s_addk_i32 s20, 0x7020
	s_mov_b32 s21, 0
	v_mov_b32_e32 v177, 0xff800000
	v_mov_b32_e32 v176, 0
	v_mov_b64_e32 v[12:13], v[138:139]
	v_mov_b64_e32 v[14:15], v[138:139]
	v_mov_b64_e32 v[4:5], v[138:139]
	v_mov_b64_e32 v[6:7], v[138:139]
	v_mov_b64_e32 v[178:179], v[166:167]
	v_mov_b64_e32 v[174:175], v[170:171]
	v_mov_b64_e32 v[168:169], v[172:173]
	v_mov_b64_e32 v[120:121], v[20:21]
	v_mov_b64_e32 v[124:125], v[28:29]
	v_mov_b64_e32 v[104:105], v[36:37]
	v_mov_b64_e32 v[108:109], v[44:45]
	v_mov_b64_e32 v[88:89], v[52:53]
	v_mov_b64_e32 v[92:93], v[68:69]
	v_mov_b64_e32 v[58:59], v[74:75]
	v_mov_b64_e32 v[62:63], v[86:87]
	v_mov_b64_e32 v[128:129], v[0:1]
	v_mov_b64_e32 v[132:133], v[8:9]
	v_mov_b64_e32 v[112:113], v[16:17]
	v_mov_b64_e32 v[116:117], v[24:25]
	v_mov_b64_e32 v[96:97], v[32:33]
	v_mov_b64_e32 v[100:101], v[40:41]
	v_mov_b64_e32 v[76:77], v[48:49]
	v_mov_b64_e32 v[80:81], v[64:65]
	v_mov_b64_e32 v[180:181], v[164:165]
	s_cmpk_eq_i32 s21, 0xe0
	s_cbranch_scc1 .LBB0_2838
	s_branch .LBB0_2828
